# FFN-in: rstd (not half-sums) cached in LDS; per-group add/fmamk/rsq and copy moves removed
# speedup vs baseline: 1.0009x; 1.0009x over previous
.LBB0_553:
	s_or_b64 exec, exec, s[54:55]
	v_mov_b32_e32 v18, v251
	v_mov_b64_e32 v[16:17], s[42:43]
	v_mad_i64_i32 v[16:17], s[54:55], v164, s31, v[16:17]
	v_mul_f32_e32 v20, 0xbfb8aa3b, v18
	v_pk_fma_f32 v[22:23], v[14:15], v[20:21], v[174:175] op_sel_hi:[1,0,1]
	v_pk_fma_f32 v[24:25], v[12:13], v[20:21], v[170:171] op_sel_hi:[1,0,1]
	v_pk_fma_f32 v[26:27], v[10:11], v[20:21], v[182:183] op_sel_hi:[1,0,1]
	v_pk_fma_f32 v[20:21], v[8:9], v[20:21], v[176:177] op_sel_hi:[1,0,1]
	v_exp_f32_e32 v26, v26
	v_exp_f32_e32 v20, v20
	v_exp_f32_e32 v21, v21
	v_exp_f32_e32 v27, v27
	v_exp_f32_e32 v24, v24
	v_exp_f32_e32 v25, v25
	v_exp_f32_e32 v22, v22
	v_exp_f32_e32 v23, v23
	v_pk_add_f32 v[26:27], v[26:27], 1.0 op_sel_hi:[1,0]
	v_pk_add_f32 v[20:21], v[20:21], 1.0 op_sel_hi:[1,0]
	v_pk_add_f32 v[24:25], v[24:25], 1.0 op_sel_hi:[1,0]
	v_pk_add_f32 v[22:23], v[22:23], 1.0 op_sel_hi:[1,0]
	v_rcp_f32_e32 v20, v20
	v_rcp_f32_e32 v21, v21
	v_rcp_f32_e32 v26, v26
	v_rcp_f32_e32 v27, v27
	v_rcp_f32_e32 v24, v24
	v_rcp_f32_e32 v25, v25
	v_rcp_f32_e32 v22, v22
	v_rcp_f32_e32 v23, v23
	v_pk_fma_f32 v[10:11], v[10:11], v[18:19], v[82:83] op_sel_hi:[1,0,1]
	v_pk_fma_f32 v[8:9], v[8:9], v[18:19], v[80:81] op_sel_hi:[1,0,1]
	v_pk_fma_f32 v[2:3], v[2:3], v[18:19], v[104:105] op_sel_hi:[1,0,1]
	v_pk_fma_f32 v[0:1], v[0:1], v[18:19], v[102:103] op_sel_hi:[1,0,1]
	v_pk_fma_f32 v[14:15], v[14:15], v[18:19], v[90:91] op_sel_hi:[1,0,1]
	v_pk_fma_f32 v[12:13], v[12:13], v[18:19], v[88:89] op_sel_hi:[1,0,1]
	v_pk_fma_f32 v[6:7], v[6:7], v[18:19], v[108:109] op_sel_hi:[1,0,1]
	v_pk_fma_f32 v[4:5], v[4:5], v[18:19], v[106:107] op_sel_hi:[1,0,1]
	v_pk_mul_f32 v[2:3], v[10:11], v[2:3]
	v_pk_mul_f32 v[0:1], v[8:9], v[0:1]
	v_lshl_add_u64 v[16:17], v[160:161], 1, v[16:17]
	v_pk_mul_f32 v[6:7], v[6:7], v[14:15]
	v_pk_mul_f32 v[4:5], v[4:5], v[12:13]
	v_pk_mul_f32 v[8:9], v[2:3], v[26:27]
	v_pk_mul_f32 v[2:3], v[0:1], v[20:21]
	s_and_b64 vcc, exec, s[40:41]
	s_mov_b32 s54, s48
	s_mov_b32 s55, s46
	s_mov_b64 s[60:61], s[52:53]
	s_mov_b64 s[58:59], s[50:51]
	v_pk_mul_f32 v[6:7], v[6:7], v[22:23]
	v_pk_mul_f32 v[4:5], v[4:5], v[24:25]
	s_nop 0
	v_cvt_pk_bf16_f32 v0, v4, v5
	v_cvt_pk_bf16_f32 v1, v6, v7
	v_cvt_pk_bf16_f32 v2, v2, v3
	v_cvt_pk_bf16_f32 v3, v8, v9
	global_store_dwordx4 v[16:17], v[0:3], off
	s_cbranch_vccnz .LBB0_572

.LBB0_556:
	v_mov_b64_e32 v[0:1], 0x420
	s_ashr_i32 s49, s48, 31
	v_cmp_lt_i64_e32 vcc, s[50:51], v[0:1]
	s_lshl_b64 s[50:51], s[48:49], 19
	s_add_u32 s50, s4, s50
	s_addc_u32 s51, s5, s51
	s_and_b64 s[52:53], vcc, exec
	s_cselect_b32 s49, s51, s59
	s_cselect_b32 s67, s50, s58
	s_ashr_i32 s47, s46, 31
	s_lshl_b64 s[52:53], s[46:47], 19
	s_add_u32 s52, s10, s52
	s_addc_u32 s53, s11, s53
	s_and_b64 s[62:63], vcc, exec
	s_cselect_b32 s47, s53, s61
	s_cselect_b32 s68, s52, s60
	s_add_u32 s58, s58, 0x40080
	s_addc_u32 s59, s59, 0
	s_add_u32 s69, s60, 0x100
	s_addc_u32 s70, s61, 0
	s_mov_b32 s71, -2
	v_add_u32_e32 v96, 0x10000, v193
	ds_read_b128 v[80:83], v96
	ds_read_b128 v[88:91], v96 offset:1024
	ds_read_b128 v[102:105], v96 offset:2048
	ds_read_b128 v[106:109], v96 offset:3072
	s_add_u32 s60, s58, 0xfffc0080
	s_addc_u32 s61, s59, -1
	s_add_i32 s72, 0, 0x10000
	v_add_u32_e32 v96, s72, v193
	s_cmp_eq_u32 s71, 12
	s_cselect_b32 s63, s49, s61
	s_cselect_b32 s62, s67, s60
	s_cselect_b32 s61, s47, s70
	s_cselect_b32 s60, s68, s69
	s_lshl_b32 s100, s54, 8
	s_lshr_b32 s101, s18, 5
	s_add_i32 s100, s100, s101
	v_add_u32_e32 v244, s100, v192
	v_lshlrev_b32_e32 v244, 6, v244
	v_mov_b32_e32 v245, 0
	v_lshl_add_u64 v[244:245], v[154:155], 0, v[244:245]
	global_load_dwordx4 v[248:251], v[244:245], off
	global_load_dwordx4 v[244:247], v[244:245], off offset:1024
	s_add_i32 m0, s27, 0xc000
	ds_read_b128 v[160:163], v195
	ds_read_b128 v[164:167], v195 offset:1024
	ds_read_b128 v[168:171], v195 offset:2048
	ds_read_b128 v[172:175], v195 offset:3072
	ds_read_b128 v[182:185], v195 offset:4096
	ds_read_b128 v[186:189], v195 offset:5120
	ds_read_b128 v[196:199], v195 offset:6144
	ds_read_b128 v[200:203], v195 offset:7168
	global_load_lds_dwordx4 v156, s[58:59]
	s_add_i32 m0, s27, 0xe000
	s_nop 0
	global_load_lds_dwordx4 v158, s[58:59]
	s_setprio 1
	s_barrier
	s_waitcnt lgkmcnt(0)
	v_mfma_f32_16x16x32_bf16 v[142:145], v[80:83], v[160:163], 0
	v_mfma_f32_16x16x32_bf16 v[138:141], v[102:105], v[160:163], 0
	v_mfma_f32_16x16x32_bf16 v[126:129], v[80:83], v[168:171], 0
	v_mfma_f32_16x16x32_bf16 v[122:125], v[102:105], v[168:171], 0
	v_mfma_f32_16x16x32_bf16 v[110:113], v[80:83], v[182:185], 0
	v_mfma_f32_16x16x32_bf16 v[98:101], v[102:105], v[182:185], 0
	v_mfma_f32_16x16x32_bf16 v[76:79], v[80:83], v[196:199], 0
	v_mfma_f32_16x16x32_bf16 v[72:75], v[102:105], v[196:199], 0
	v_mfma_f32_16x16x32_bf16 v[142:145], v[88:91], v[164:167], v[142:145]
	v_mfma_f32_16x16x32_bf16 v[138:141], v[106:109], v[164:167], v[138:141]
	v_mfma_f32_16x16x32_bf16 v[126:129], v[88:91], v[172:175], v[126:129]
	v_mfma_f32_16x16x32_bf16 v[122:125], v[106:109], v[172:175], v[122:125]
	v_mfma_f32_16x16x32_bf16 v[110:113], v[88:91], v[186:189], v[110:113]
	v_mfma_f32_16x16x32_bf16 v[98:101], v[106:109], v[186:189], v[98:101]
	v_mfma_f32_16x16x32_bf16 v[76:79], v[88:91], v[200:203], v[76:79]
	v_mfma_f32_16x16x32_bf16 v[72:75], v[106:109], v[200:203], v[72:75]
	s_barrier
	s_setprio 0
	s_add_i32 s76, 0, 0x14000
	s_add_i32 s72, s72, s18
	v_add_u32_e32 v96, s76, v193
	v_lshl_add_u64 v[176:177], s[60:61], 0, v[150:151]
	s_mov_b32 m0, s72
	ds_read_b128 v[224:227], v96
	ds_read_b128 v[228:231], v96 offset:1024
	ds_read_b128 v[232:235], v96 offset:2048
	ds_read_b128 v[236:239], v96 offset:3072
	global_load_lds_dwordx4 v150, s[60:61]
	v_lshl_add_u64 v[190:191], s[60:61], 0, v[146:147]
	s_add_i32 m0, s72, 0x2000
	s_nop 0
	global_load_lds_dwordx4 v146, s[60:61]
	s_setprio 1
	s_barrier
	s_waitcnt lgkmcnt(0)
	v_mfma_f32_16x16x32_bf16 v[134:137], v[224:227], v[160:163], 0
	v_mfma_f32_16x16x32_bf16 v[130:133], v[232:235], v[160:163], 0
	v_mfma_f32_16x16x32_bf16 v[118:121], v[224:227], v[168:171], 0
	s_mov_b32 m0, s27
	v_mfma_f32_16x16x32_bf16 v[114:117], v[232:235], v[168:171], 0
	v_lshl_add_u64 v[240:241], s[62:63], 0, v[152:153]
	v_mfma_f32_16x16x32_bf16 v[92:95], v[224:227], v[182:185], 0
	v_mfma_f32_16x16x32_bf16 v[84:87], v[232:235], v[182:185], 0
	v_mfma_f32_16x16x32_bf16 v[68:71], v[224:227], v[196:199], 0
	v_mfma_f32_16x16x32_bf16 v[64:67], v[232:235], v[196:199], 0
	v_mfma_f32_16x16x32_bf16 v[134:137], v[228:231], v[164:167], v[134:137]
	v_mfma_f32_16x16x32_bf16 v[130:133], v[236:239], v[164:167], v[130:133]
	v_mfma_f32_16x16x32_bf16 v[118:121], v[228:231], v[172:175], v[118:121]
	v_mfma_f32_16x16x32_bf16 v[114:117], v[236:239], v[172:175], v[114:117]
	v_mfma_f32_16x16x32_bf16 v[92:95], v[228:231], v[186:189], v[92:95]
	v_mfma_f32_16x16x32_bf16 v[84:87], v[236:239], v[186:189], v[84:87]
	v_mfma_f32_16x16x32_bf16 v[68:71], v[228:231], v[200:203], v[68:71]
	v_mfma_f32_16x16x32_bf16 v[64:67], v[236:239], v[200:203], v[64:67]
	s_barrier
	s_setprio 0
	ds_read_b128 v[160:163], v195 offset:16384
	ds_read_b128 v[164:167], v195 offset:17408
	ds_read_b128 v[168:171], v195 offset:18432
	ds_read_b128 v[172:175], v195 offset:19456
	ds_read_b128 v[182:185], v195 offset:20480
	ds_read_b128 v[186:189], v195 offset:21504
	ds_read_b128 v[196:199], v195 offset:22528
	ds_read_b128 v[200:203], v195 offset:23552
	global_load_lds_dwordx4 v152, s[62:63]
	v_lshl_add_u64 v[242:243], s[62:63], 0, v[148:149]
	s_mov_b32 m0, s28
	s_nop 0
	global_load_lds_dwordx4 v148, s[62:63]
	s_waitcnt vmcnt(12)
	s_setprio 1
	s_barrier
	s_waitcnt lgkmcnt(0)
	v_mfma_f32_16x16x32_bf16 v[60:63], v[80:83], v[160:163], 0
	v_mfma_f32_16x16x32_bf16 v[56:59], v[102:105], v[160:163], 0
	v_mfma_f32_16x16x32_bf16 v[44:47], v[80:83], v[168:171], 0
	v_mfma_f32_16x16x32_bf16 v[40:43], v[102:105], v[168:171], 0
	v_mfma_f32_16x16x32_bf16 v[28:31], v[80:83], v[182:185], 0
	v_mfma_f32_16x16x32_bf16 v[24:27], v[102:105], v[182:185], 0
	v_mfma_f32_16x16x32_bf16 v[12:15], v[80:83], v[196:199], 0
	v_mfma_f32_16x16x32_bf16 v[8:11], v[102:105], v[196:199], 0
	v_mfma_f32_16x16x32_bf16 v[60:63], v[88:91], v[164:167], v[60:63]
	v_mfma_f32_16x16x32_bf16 v[56:59], v[106:109], v[164:167], v[56:59]
	v_mfma_f32_16x16x32_bf16 v[44:47], v[88:91], v[172:175], v[44:47]
	v_mfma_f32_16x16x32_bf16 v[40:43], v[106:109], v[172:175], v[40:43]
	v_mfma_f32_16x16x32_bf16 v[28:31], v[88:91], v[186:189], v[28:31]
	v_mfma_f32_16x16x32_bf16 v[24:27], v[106:109], v[186:189], v[24:27]
	v_mfma_f32_16x16x32_bf16 v[12:15], v[88:91], v[200:203], v[12:15]
	v_mfma_f32_16x16x32_bf16 v[8:11], v[106:109], v[200:203], v[8:11]
	s_barrier
	s_setprio 0
	v_add_u32_e32 v96, 0x18000, v193
	ds_read_b128 v[80:83], v96
	ds_read_b128 v[88:91], v96 offset:1024
	ds_read_b128 v[102:105], v96 offset:2048
	ds_read_b128 v[106:109], v96 offset:3072
	s_add_u32 s74, s60, 0x40000
	s_addc_u32 s75, s61, 0
	s_add_i32 s72, s76, s18
	s_mov_b32 m0, s72
	s_nop 0
	global_load_lds_dwordx4 v150, s[74:75]
	s_add_i32 m0, s72, 0x2000
	s_nop 0
	global_load_lds_dwordx4 v146, s[74:75]
	s_waitcnt vmcnt(6)
	s_setprio 1
	s_barrier
	v_mfma_f32_16x16x32_bf16 v[52:55], v[224:227], v[160:163], 0
	v_add_f32_e32 v248, v248, v249
	v_add_f32_e32 v250, v250, v251
	v_add_f32_e32 v248, v248, v250
	v_add_f32_e32 v244, v244, v245
	v_add_f32_e32 v246, v246, v247
	v_add_f32_e32 v244, v244, v246
	v_mov_b32_e32 v249, v248
	v_mov_b32_e32 v245, v244
	s_nop 1
	v_permlane16_swap_b32_e32 v248, v249
	v_permlane16_swap_b32_e32 v244, v245
	s_nop 1
	v_add_f32_e32 v248, v248, v249
	v_add_f32_e32 v244, v244, v245
	v_mov_b32_e32 v249, v248
	v_mov_b32_e32 v245, v244
	s_nop 1
	v_permlane32_swap_b32_e32 v248, v249
	v_permlane32_swap_b32_e32 v244, v245
	s_nop 1
	v_add_f32_e32 v248, v248, v249
	v_add_f32_e32 v244, v244, v245
	v_fmamk_f32 v248, v248, 0x3a800000, v207
	v_fmamk_f32 v244, v244, 0x3a800000, v207
	v_rsq_f32_e32 v248, v248
	v_rsq_f32_e32 v244, v244
	s_nop 1
	s_lshr_b32 s101, s18, 3
	s_add_i32 s101, s101, 0x20000
	v_lshl_add_u32 v250, v192, 2, s101
	ds_write_b32 v250, v248
	ds_write_b32 v250, v244 offset:64
	v_mfma_f32_16x16x32_bf16 v[48:51], v[232:235], v[160:163], 0
	v_mfma_f32_16x16x32_bf16 v[36:39], v[224:227], v[168:171], 0
	s_add_i32 s72, 0, 0x18000
	v_mfma_f32_16x16x32_bf16 v[32:35], v[232:235], v[168:171], 0
	v_add_u32_e32 v96, s72, v193
	v_mfma_f32_16x16x32_bf16 v[20:23], v[224:227], v[182:185], 0
	v_mfma_f32_16x16x32_bf16 v[16:19], v[232:235], v[182:185], 0
	v_mfma_f32_16x16x32_bf16 v[4:7], v[224:227], v[196:199], 0
	v_mfma_f32_16x16x32_bf16 v[0:3], v[232:235], v[196:199], 0
	v_mfma_f32_16x16x32_bf16 v[52:55], v[228:231], v[164:167], v[52:55]
	v_mfma_f32_16x16x32_bf16 v[48:51], v[236:239], v[164:167], v[48:51]
	v_mfma_f32_16x16x32_bf16 v[36:39], v[228:231], v[172:175], v[36:39]
	v_mfma_f32_16x16x32_bf16 v[32:35], v[236:239], v[172:175], v[32:35]
	v_mfma_f32_16x16x32_bf16 v[20:23], v[228:231], v[186:189], v[20:23]
	v_mfma_f32_16x16x32_bf16 v[16:19], v[236:239], v[186:189], v[16:19]
	v_mfma_f32_16x16x32_bf16 v[4:7], v[228:231], v[200:203], v[4:7]
	v_mfma_f32_16x16x32_bf16 v[0:3], v[236:239], v[200:203], v[0:3]
	s_barrier
	s_setprio 0
	s_add_u32 s62, s62, 0x40000
	s_addc_u32 s63, s63, 0
	s_mov_b32 m0, s37
	ds_read_b128 v[160:163], v195 offset:32768
	ds_read_b128 v[164:167], v195 offset:33792
	ds_read_b128 v[168:171], v195 offset:34816
	ds_read_b128 v[172:175], v195 offset:35840
	ds_read_b128 v[182:185], v195 offset:36864
	ds_read_b128 v[186:189], v195 offset:37888
	ds_read_b128 v[196:199], v195 offset:38912
	ds_read_b128 v[200:203], v195 offset:39936
	global_load_lds_dwordx4 v152, s[62:63]
	s_mov_b32 m0, s56
	s_nop 0
	global_load_lds_dwordx4 v148, s[62:63]
	s_setprio 1
	s_barrier
	s_waitcnt lgkmcnt(0)
	v_mfma_f32_16x16x32_bf16 v[142:145], v[80:83], v[160:163], v[142:145]
	v_mfma_f32_16x16x32_bf16 v[138:141], v[102:105], v[160:163], v[138:141]
	v_mfma_f32_16x16x32_bf16 v[126:129], v[80:83], v[168:171], v[126:129]
	v_mfma_f32_16x16x32_bf16 v[122:125], v[102:105], v[168:171], v[122:125]
	v_mfma_f32_16x16x32_bf16 v[110:113], v[80:83], v[182:185], v[110:113]
	v_mfma_f32_16x16x32_bf16 v[98:101], v[102:105], v[182:185], v[98:101]
	v_mfma_f32_16x16x32_bf16 v[76:79], v[80:83], v[196:199], v[76:79]
	v_mfma_f32_16x16x32_bf16 v[72:75], v[102:105], v[196:199], v[72:75]
	v_mfma_f32_16x16x32_bf16 v[142:145], v[88:91], v[164:167], v[142:145]
	v_mfma_f32_16x16x32_bf16 v[138:141], v[106:109], v[164:167], v[138:141]
	v_mfma_f32_16x16x32_bf16 v[126:129], v[88:91], v[172:175], v[126:129]
	v_mfma_f32_16x16x32_bf16 v[122:125], v[106:109], v[172:175], v[122:125]
	v_mfma_f32_16x16x32_bf16 v[110:113], v[88:91], v[186:189], v[110:113]
	v_mfma_f32_16x16x32_bf16 v[98:101], v[106:109], v[186:189], v[98:101]
	v_mfma_f32_16x16x32_bf16 v[76:79], v[88:91], v[200:203], v[76:79]
	v_mfma_f32_16x16x32_bf16 v[72:75], v[106:109], v[200:203], v[72:75]
	s_barrier
	s_setprio 0
	s_add_i32 s62, 0, 0x1c000
	s_add_i32 s63, s72, s18
	v_add_u32_e32 v96, s62, v193
	v_lshl_add_u64 v[176:177], v[176:177], 0, s[6:7]
	s_mov_b32 m0, s63
	ds_read_b128 v[224:227], v96
	ds_read_b128 v[228:231], v96 offset:1024
	ds_read_b128 v[232:235], v96 offset:2048
	ds_read_b128 v[236:239], v96 offset:3072
	global_load_lds_dwordx4 v[176:177], off
	v_lshl_add_u64 v[176:177], v[190:191], 0, s[6:7]
	s_add_i32 m0, s63, 0x2000
	s_nop 0
	global_load_lds_dwordx4 v[176:177], off
	s_setprio 1
	s_barrier
	s_waitcnt lgkmcnt(0)
	v_mfma_f32_16x16x32_bf16 v[134:137], v[224:227], v[160:163], v[134:137]
	v_mfma_f32_16x16x32_bf16 v[130:133], v[232:235], v[160:163], v[130:133]
	v_mfma_f32_16x16x32_bf16 v[118:121], v[224:227], v[168:171], v[118:121]
	s_mov_b32 m0, s64
	v_mfma_f32_16x16x32_bf16 v[114:117], v[232:235], v[168:171], v[114:117]
	v_lshl_add_u64 v[176:177], v[240:241], 0, s[6:7]
	v_mfma_f32_16x16x32_bf16 v[92:95], v[224:227], v[182:185], v[92:95]
	v_mfma_f32_16x16x32_bf16 v[84:87], v[232:235], v[182:185], v[84:87]
	v_mfma_f32_16x16x32_bf16 v[68:71], v[224:227], v[196:199], v[68:71]
	v_mfma_f32_16x16x32_bf16 v[64:67], v[232:235], v[196:199], v[64:67]
	v_mfma_f32_16x16x32_bf16 v[134:137], v[228:231], v[164:167], v[134:137]
	v_mfma_f32_16x16x32_bf16 v[130:133], v[236:239], v[164:167], v[130:133]
	v_mfma_f32_16x16x32_bf16 v[118:121], v[228:231], v[172:175], v[118:121]
	v_mfma_f32_16x16x32_bf16 v[114:117], v[236:239], v[172:175], v[114:117]
	v_mfma_f32_16x16x32_bf16 v[92:95], v[228:231], v[186:189], v[92:95]
	v_mfma_f32_16x16x32_bf16 v[84:87], v[236:239], v[186:189], v[84:87]
	v_mfma_f32_16x16x32_bf16 v[68:71], v[228:231], v[200:203], v[68:71]
	v_mfma_f32_16x16x32_bf16 v[64:67], v[236:239], v[200:203], v[64:67]
	s_barrier
	s_setprio 0
	ds_read_b128 v[160:163], v195 offset:49152
	ds_read_b128 v[164:167], v195 offset:50176
	ds_read_b128 v[168:171], v195 offset:51200
	ds_read_b128 v[172:175], v195 offset:52224
	ds_read_b128 v[182:185], v195 offset:53248
	ds_read_b128 v[186:189], v195 offset:54272
	ds_read_b128 v[196:199], v195 offset:55296
	ds_read_b128 v[200:203], v195 offset:56320
	global_load_lds_dwordx4 v[176:177], off
	v_lshl_add_u64 v[176:177], v[242:243], 0, s[6:7]
	s_mov_b32 m0, s65
	s_nop 0
	global_load_lds_dwordx4 v[176:177], off
	s_waitcnt vmcnt(10)
	s_setprio 1
	s_barrier
	s_waitcnt lgkmcnt(0)
	v_mfma_f32_16x16x32_bf16 v[60:63], v[80:83], v[160:163], v[60:63]
	v_mfma_f32_16x16x32_bf16 v[56:59], v[102:105], v[160:163], v[56:59]
	v_mfma_f32_16x16x32_bf16 v[44:47], v[80:83], v[168:171], v[44:47]
	v_mfma_f32_16x16x32_bf16 v[40:43], v[102:105], v[168:171], v[40:43]
	v_mfma_f32_16x16x32_bf16 v[28:31], v[80:83], v[182:185], v[28:31]
	v_mfma_f32_16x16x32_bf16 v[24:27], v[102:105], v[182:185], v[24:27]
	v_mfma_f32_16x16x32_bf16 v[12:15], v[80:83], v[196:199], v[12:15]
	v_mfma_f32_16x16x32_bf16 v[8:11], v[102:105], v[196:199], v[8:11]
	v_mfma_f32_16x16x32_bf16 v[60:63], v[88:91], v[164:167], v[60:63]
	v_mfma_f32_16x16x32_bf16 v[56:59], v[106:109], v[164:167], v[56:59]
	v_mfma_f32_16x16x32_bf16 v[44:47], v[88:91], v[172:175], v[44:47]
	v_mfma_f32_16x16x32_bf16 v[40:43], v[106:109], v[172:175], v[40:43]
	v_mfma_f32_16x16x32_bf16 v[28:31], v[88:91], v[186:189], v[28:31]
	v_mfma_f32_16x16x32_bf16 v[24:27], v[106:109], v[186:189], v[24:27]
	v_mfma_f32_16x16x32_bf16 v[12:15], v[88:91], v[200:203], v[12:15]
	v_mfma_f32_16x16x32_bf16 v[8:11], v[106:109], v[200:203], v[8:11]
	s_barrier
	s_setprio 0
	v_add_u32_e32 v96, 0x10000, v193
	ds_read_b128 v[80:83], v96
	ds_read_b128 v[88:91], v96 offset:1024
	ds_read_b128 v[102:105], v96 offset:2048
	ds_read_b128 v[106:109], v96 offset:3072
	s_add_u32 s60, s60, 0x40080
	s_addc_u32 s61, s61, 0
	s_add_i32 s62, s62, s18
	s_mov_b32 m0, s62
	s_nop 0
	global_load_lds_dwordx4 v150, s[60:61]
	s_add_i32 m0, s62, 0x2000
	s_nop 0
	global_load_lds_dwordx4 v146, s[60:61]
	s_waitcnt vmcnt(6)
	s_setprio 1
	s_barrier
	v_mfma_f32_16x16x32_bf16 v[52:55], v[224:227], v[160:163], v[52:55]
	v_mfma_f32_16x16x32_bf16 v[48:51], v[232:235], v[160:163], v[48:51]
	v_mfma_f32_16x16x32_bf16 v[36:39], v[224:227], v[168:171], v[36:39]
	s_add_i32 s71, s71, 2
	v_mfma_f32_16x16x32_bf16 v[32:35], v[232:235], v[168:171], v[32:35]
	s_add_u32 s58, s58, 0x100
	v_mfma_f32_16x16x32_bf16 v[20:23], v[224:227], v[182:185], v[20:23]
	s_addc_u32 s59, s59, 0
	v_mfma_f32_16x16x32_bf16 v[16:19], v[232:235], v[182:185], v[16:19]
	s_add_u32 s69, s69, 0x100
	v_mfma_f32_16x16x32_bf16 v[4:7], v[224:227], v[196:199], v[4:7]
	s_addc_u32 s70, s70, 0
	v_mfma_f32_16x16x32_bf16 v[0:3], v[232:235], v[196:199], v[0:3]
	s_cmp_gt_u32 s71, 13
	v_mfma_f32_16x16x32_bf16 v[52:55], v[228:231], v[164:167], v[52:55]
	v_mfma_f32_16x16x32_bf16 v[48:51], v[236:239], v[164:167], v[48:51]
	v_mfma_f32_16x16x32_bf16 v[36:39], v[228:231], v[172:175], v[36:39]
	v_mfma_f32_16x16x32_bf16 v[32:35], v[236:239], v[172:175], v[32:35]
	v_mfma_f32_16x16x32_bf16 v[20:23], v[228:231], v[186:189], v[20:23]
	v_mfma_f32_16x16x32_bf16 v[16:19], v[236:239], v[186:189], v[16:19]
	v_mfma_f32_16x16x32_bf16 v[4:7], v[228:231], v[200:203], v[4:7]
	v_mfma_f32_16x16x32_bf16 v[0:3], v[236:239], v[200:203], v[0:3]
	s_barrier
	s_setprio 0
.LBB0_557:
	s_add_u32 s60, s58, 0xfffc0080
	s_addc_u32 s61, s59, -1
	s_add_i32 s72, 0, 0x10000
	v_add_u32_e32 v96, s72, v193
	s_cmp_eq_u32 s71, 12
	s_cselect_b32 s63, s49, s61
	s_cselect_b32 s62, s67, s60
	s_cselect_b32 s61, s47, s70
	s_cselect_b32 s60, s68, s69
	s_add_i32 m0, s27, 0xc000
	ds_read_b128 v[160:163], v195
	ds_read_b128 v[164:167], v195 offset:1024
	ds_read_b128 v[168:171], v195 offset:2048
	ds_read_b128 v[172:175], v195 offset:3072
	ds_read_b128 v[182:185], v195 offset:4096
	ds_read_b128 v[186:189], v195 offset:5120
	ds_read_b128 v[196:199], v195 offset:6144
	ds_read_b128 v[200:203], v195 offset:7168
	global_load_lds_dwordx4 v156, s[58:59]
	s_add_i32 m0, s27, 0xe000
	s_nop 0
	global_load_lds_dwordx4 v158, s[58:59]
	s_setprio 1
	s_barrier
	s_waitcnt lgkmcnt(0)
	v_mfma_f32_16x16x32_bf16 v[142:145], v[80:83], v[160:163], v[142:145]
	v_mfma_f32_16x16x32_bf16 v[138:141], v[102:105], v[160:163], v[138:141]
	v_mfma_f32_16x16x32_bf16 v[126:129], v[80:83], v[168:171], v[126:129]
	v_mfma_f32_16x16x32_bf16 v[122:125], v[102:105], v[168:171], v[122:125]
	v_mfma_f32_16x16x32_bf16 v[110:113], v[80:83], v[182:185], v[110:113]
	v_mfma_f32_16x16x32_bf16 v[98:101], v[102:105], v[182:185], v[98:101]
	v_mfma_f32_16x16x32_bf16 v[76:79], v[80:83], v[196:199], v[76:79]
	v_mfma_f32_16x16x32_bf16 v[72:75], v[102:105], v[196:199], v[72:75]
	v_mfma_f32_16x16x32_bf16 v[142:145], v[88:91], v[164:167], v[142:145]
	v_mfma_f32_16x16x32_bf16 v[138:141], v[106:109], v[164:167], v[138:141]
	v_mfma_f32_16x16x32_bf16 v[126:129], v[88:91], v[172:175], v[126:129]
	v_mfma_f32_16x16x32_bf16 v[122:125], v[106:109], v[172:175], v[122:125]
	v_mfma_f32_16x16x32_bf16 v[110:113], v[88:91], v[186:189], v[110:113]
	v_mfma_f32_16x16x32_bf16 v[98:101], v[106:109], v[186:189], v[98:101]
	v_mfma_f32_16x16x32_bf16 v[76:79], v[88:91], v[200:203], v[76:79]
	v_mfma_f32_16x16x32_bf16 v[72:75], v[106:109], v[200:203], v[72:75]
	s_barrier
	s_setprio 0
	s_add_i32 s76, 0, 0x14000
	s_add_i32 s72, s72, s18
	v_add_u32_e32 v96, s76, v193
	v_lshl_add_u64 v[176:177], s[60:61], 0, v[150:151]
	s_mov_b32 m0, s72
	ds_read_b128 v[224:227], v96
	ds_read_b128 v[228:231], v96 offset:1024
	ds_read_b128 v[232:235], v96 offset:2048
	ds_read_b128 v[236:239], v96 offset:3072
	global_load_lds_dwordx4 v150, s[60:61]
	v_lshl_add_u64 v[190:191], s[60:61], 0, v[146:147]
	s_add_i32 m0, s72, 0x2000
	s_nop 0
	global_load_lds_dwordx4 v146, s[60:61]
	s_setprio 1
	s_barrier
	s_waitcnt lgkmcnt(0)
	v_mfma_f32_16x16x32_bf16 v[134:137], v[224:227], v[160:163], v[134:137]
	v_mfma_f32_16x16x32_bf16 v[130:133], v[232:235], v[160:163], v[130:133]
	v_mfma_f32_16x16x32_bf16 v[118:121], v[224:227], v[168:171], v[118:121]
	s_mov_b32 m0, s27
	v_mfma_f32_16x16x32_bf16 v[114:117], v[232:235], v[168:171], v[114:117]
	v_lshl_add_u64 v[240:241], s[62:63], 0, v[152:153]
	v_mfma_f32_16x16x32_bf16 v[92:95], v[224:227], v[182:185], v[92:95]
	v_mfma_f32_16x16x32_bf16 v[84:87], v[232:235], v[182:185], v[84:87]
	v_mfma_f32_16x16x32_bf16 v[68:71], v[224:227], v[196:199], v[68:71]
	v_mfma_f32_16x16x32_bf16 v[64:67], v[232:235], v[196:199], v[64:67]
	v_mfma_f32_16x16x32_bf16 v[134:137], v[228:231], v[164:167], v[134:137]
	v_mfma_f32_16x16x32_bf16 v[130:133], v[236:239], v[164:167], v[130:133]
	v_mfma_f32_16x16x32_bf16 v[118:121], v[228:231], v[172:175], v[118:121]
	v_mfma_f32_16x16x32_bf16 v[114:117], v[236:239], v[172:175], v[114:117]
	v_mfma_f32_16x16x32_bf16 v[92:95], v[228:231], v[186:189], v[92:95]
	v_mfma_f32_16x16x32_bf16 v[84:87], v[236:239], v[186:189], v[84:87]
	v_mfma_f32_16x16x32_bf16 v[68:71], v[228:231], v[200:203], v[68:71]
	v_mfma_f32_16x16x32_bf16 v[64:67], v[236:239], v[200:203], v[64:67]
	s_barrier
	s_setprio 0
	ds_read_b128 v[160:163], v195 offset:16384
	ds_read_b128 v[164:167], v195 offset:17408
	ds_read_b128 v[168:171], v195 offset:18432
	ds_read_b128 v[172:175], v195 offset:19456
	ds_read_b128 v[182:185], v195 offset:20480
	ds_read_b128 v[186:189], v195 offset:21504
	ds_read_b128 v[196:199], v195 offset:22528
	ds_read_b128 v[200:203], v195 offset:23552
	global_load_lds_dwordx4 v152, s[62:63]
	v_lshl_add_u64 v[242:243], s[62:63], 0, v[148:149]
	s_mov_b32 m0, s28
	s_nop 0
	global_load_lds_dwordx4 v148, s[62:63]
	s_waitcnt vmcnt(10)
	s_setprio 1
	s_barrier
	s_waitcnt lgkmcnt(0)
	v_mfma_f32_16x16x32_bf16 v[60:63], v[80:83], v[160:163], v[60:63]
	v_mfma_f32_16x16x32_bf16 v[56:59], v[102:105], v[160:163], v[56:59]
	v_mfma_f32_16x16x32_bf16 v[44:47], v[80:83], v[168:171], v[44:47]
	v_mfma_f32_16x16x32_bf16 v[40:43], v[102:105], v[168:171], v[40:43]
	v_mfma_f32_16x16x32_bf16 v[28:31], v[80:83], v[182:185], v[28:31]
	v_mfma_f32_16x16x32_bf16 v[24:27], v[102:105], v[182:185], v[24:27]
	v_mfma_f32_16x16x32_bf16 v[12:15], v[80:83], v[196:199], v[12:15]
	v_mfma_f32_16x16x32_bf16 v[8:11], v[102:105], v[196:199], v[8:11]
	v_mfma_f32_16x16x32_bf16 v[60:63], v[88:91], v[164:167], v[60:63]
	v_mfma_f32_16x16x32_bf16 v[56:59], v[106:109], v[164:167], v[56:59]
	v_mfma_f32_16x16x32_bf16 v[44:47], v[88:91], v[172:175], v[44:47]
	v_mfma_f32_16x16x32_bf16 v[40:43], v[106:109], v[172:175], v[40:43]
	v_mfma_f32_16x16x32_bf16 v[28:31], v[88:91], v[186:189], v[28:31]
	v_mfma_f32_16x16x32_bf16 v[24:27], v[106:109], v[186:189], v[24:27]
	v_mfma_f32_16x16x32_bf16 v[12:15], v[88:91], v[200:203], v[12:15]
	v_mfma_f32_16x16x32_bf16 v[8:11], v[106:109], v[200:203], v[8:11]
	s_barrier
	s_setprio 0
	v_add_u32_e32 v96, 0x18000, v193
	ds_read_b128 v[80:83], v96
	ds_read_b128 v[88:91], v96 offset:1024
	ds_read_b128 v[102:105], v96 offset:2048
	ds_read_b128 v[106:109], v96 offset:3072
	s_add_u32 s74, s60, 0x40000
	s_addc_u32 s75, s61, 0
	s_add_i32 s72, s76, s18
	s_mov_b32 m0, s72
	s_nop 0
	global_load_lds_dwordx4 v150, s[74:75]
	s_add_i32 m0, s72, 0x2000
	s_nop 0
	global_load_lds_dwordx4 v146, s[74:75]
	s_waitcnt vmcnt(6)
	s_setprio 1
	s_barrier
	v_mfma_f32_16x16x32_bf16 v[52:55], v[224:227], v[160:163], v[52:55]
	v_mfma_f32_16x16x32_bf16 v[48:51], v[232:235], v[160:163], v[48:51]
	v_mfma_f32_16x16x32_bf16 v[36:39], v[224:227], v[168:171], v[36:39]
	s_add_i32 s72, 0, 0x18000
	v_mfma_f32_16x16x32_bf16 v[32:35], v[232:235], v[168:171], v[32:35]
	v_add_u32_e32 v96, s72, v193
	v_mfma_f32_16x16x32_bf16 v[20:23], v[224:227], v[182:185], v[20:23]
	v_mfma_f32_16x16x32_bf16 v[16:19], v[232:235], v[182:185], v[16:19]
	v_mfma_f32_16x16x32_bf16 v[4:7], v[224:227], v[196:199], v[4:7]
	v_mfma_f32_16x16x32_bf16 v[0:3], v[232:235], v[196:199], v[0:3]
	v_mfma_f32_16x16x32_bf16 v[52:55], v[228:231], v[164:167], v[52:55]
	v_mfma_f32_16x16x32_bf16 v[48:51], v[236:239], v[164:167], v[48:51]
	v_mfma_f32_16x16x32_bf16 v[36:39], v[228:231], v[172:175], v[36:39]
	v_mfma_f32_16x16x32_bf16 v[32:35], v[236:239], v[172:175], v[32:35]
	v_mfma_f32_16x16x32_bf16 v[20:23], v[228:231], v[186:189], v[20:23]
	v_mfma_f32_16x16x32_bf16 v[16:19], v[236:239], v[186:189], v[16:19]
	v_mfma_f32_16x16x32_bf16 v[4:7], v[228:231], v[200:203], v[4:7]
	v_mfma_f32_16x16x32_bf16 v[0:3], v[236:239], v[200:203], v[0:3]
	s_barrier
	s_setprio 0
	s_add_u32 s62, s62, 0x40000
	s_addc_u32 s63, s63, 0
	s_mov_b32 m0, s37
	ds_read_b128 v[160:163], v195 offset:32768
	ds_read_b128 v[164:167], v195 offset:33792
	ds_read_b128 v[168:171], v195 offset:34816
	ds_read_b128 v[172:175], v195 offset:35840
	ds_read_b128 v[182:185], v195 offset:36864
	ds_read_b128 v[186:189], v195 offset:37888
	ds_read_b128 v[196:199], v195 offset:38912
	ds_read_b128 v[200:203], v195 offset:39936
	global_load_lds_dwordx4 v152, s[62:63]
	s_mov_b32 m0, s56
	s_nop 0
	global_load_lds_dwordx4 v148, s[62:63]
	s_setprio 1
	s_barrier
	s_waitcnt lgkmcnt(0)
	v_mfma_f32_16x16x32_bf16 v[142:145], v[80:83], v[160:163], v[142:145]
	v_mfma_f32_16x16x32_bf16 v[138:141], v[102:105], v[160:163], v[138:141]
	v_mfma_f32_16x16x32_bf16 v[126:129], v[80:83], v[168:171], v[126:129]
	v_mfma_f32_16x16x32_bf16 v[122:125], v[102:105], v[168:171], v[122:125]
	v_mfma_f32_16x16x32_bf16 v[110:113], v[80:83], v[182:185], v[110:113]
	v_mfma_f32_16x16x32_bf16 v[98:101], v[102:105], v[182:185], v[98:101]
	v_mfma_f32_16x16x32_bf16 v[76:79], v[80:83], v[196:199], v[76:79]
	v_mfma_f32_16x16x32_bf16 v[72:75], v[102:105], v[196:199], v[72:75]
	v_mfma_f32_16x16x32_bf16 v[142:145], v[88:91], v[164:167], v[142:145]
	v_mfma_f32_16x16x32_bf16 v[138:141], v[106:109], v[164:167], v[138:141]
	v_mfma_f32_16x16x32_bf16 v[126:129], v[88:91], v[172:175], v[126:129]
	v_mfma_f32_16x16x32_bf16 v[122:125], v[106:109], v[172:175], v[122:125]
	v_mfma_f32_16x16x32_bf16 v[110:113], v[88:91], v[186:189], v[110:113]
	v_mfma_f32_16x16x32_bf16 v[98:101], v[106:109], v[186:189], v[98:101]
	v_mfma_f32_16x16x32_bf16 v[76:79], v[88:91], v[200:203], v[76:79]
	v_mfma_f32_16x16x32_bf16 v[72:75], v[106:109], v[200:203], v[72:75]
	s_barrier
	s_setprio 0
	s_add_i32 s62, 0, 0x1c000
	s_add_i32 s63, s72, s18
	v_add_u32_e32 v96, s62, v193
	v_lshl_add_u64 v[176:177], v[176:177], 0, s[6:7]
	s_mov_b32 m0, s63
	ds_read_b128 v[224:227], v96
	ds_read_b128 v[228:231], v96 offset:1024
	ds_read_b128 v[232:235], v96 offset:2048
	ds_read_b128 v[236:239], v96 offset:3072
	global_load_lds_dwordx4 v[176:177], off
	v_lshl_add_u64 v[176:177], v[190:191], 0, s[6:7]
	s_add_i32 m0, s63, 0x2000
	s_nop 0
	global_load_lds_dwordx4 v[176:177], off
	s_setprio 1
	s_barrier
	s_waitcnt lgkmcnt(0)
	v_mfma_f32_16x16x32_bf16 v[134:137], v[224:227], v[160:163], v[134:137]
	v_mfma_f32_16x16x32_bf16 v[130:133], v[232:235], v[160:163], v[130:133]
	v_mfma_f32_16x16x32_bf16 v[118:121], v[224:227], v[168:171], v[118:121]
	s_mov_b32 m0, s64
	v_mfma_f32_16x16x32_bf16 v[114:117], v[232:235], v[168:171], v[114:117]
	v_lshl_add_u64 v[176:177], v[240:241], 0, s[6:7]
	v_mfma_f32_16x16x32_bf16 v[92:95], v[224:227], v[182:185], v[92:95]
	v_mfma_f32_16x16x32_bf16 v[84:87], v[232:235], v[182:185], v[84:87]
	v_mfma_f32_16x16x32_bf16 v[68:71], v[224:227], v[196:199], v[68:71]
	v_mfma_f32_16x16x32_bf16 v[64:67], v[232:235], v[196:199], v[64:67]
	v_mfma_f32_16x16x32_bf16 v[134:137], v[228:231], v[164:167], v[134:137]
	v_mfma_f32_16x16x32_bf16 v[130:133], v[236:239], v[164:167], v[130:133]
	v_mfma_f32_16x16x32_bf16 v[118:121], v[228:231], v[172:175], v[118:121]
	v_mfma_f32_16x16x32_bf16 v[114:117], v[236:239], v[172:175], v[114:117]
	v_mfma_f32_16x16x32_bf16 v[92:95], v[228:231], v[186:189], v[92:95]
	v_mfma_f32_16x16x32_bf16 v[84:87], v[236:239], v[186:189], v[84:87]
	v_mfma_f32_16x16x32_bf16 v[68:71], v[228:231], v[200:203], v[68:71]
	v_mfma_f32_16x16x32_bf16 v[64:67], v[236:239], v[200:203], v[64:67]
	s_barrier
	s_setprio 0
	ds_read_b128 v[160:163], v195 offset:49152
	ds_read_b128 v[164:167], v195 offset:50176
	ds_read_b128 v[168:171], v195 offset:51200
	ds_read_b128 v[172:175], v195 offset:52224
	ds_read_b128 v[182:185], v195 offset:53248
	ds_read_b128 v[186:189], v195 offset:54272
	ds_read_b128 v[196:199], v195 offset:55296
	ds_read_b128 v[200:203], v195 offset:56320
	global_load_lds_dwordx4 v[176:177], off
	v_lshl_add_u64 v[176:177], v[242:243], 0, s[6:7]
	s_mov_b32 m0, s65
	s_nop 0
	global_load_lds_dwordx4 v[176:177], off
	s_waitcnt vmcnt(10)
	s_setprio 1
	s_barrier
	s_waitcnt lgkmcnt(0)
	v_mfma_f32_16x16x32_bf16 v[60:63], v[80:83], v[160:163], v[60:63]
	v_mfma_f32_16x16x32_bf16 v[56:59], v[102:105], v[160:163], v[56:59]
	v_mfma_f32_16x16x32_bf16 v[44:47], v[80:83], v[168:171], v[44:47]
	v_mfma_f32_16x16x32_bf16 v[40:43], v[102:105], v[168:171], v[40:43]
	v_mfma_f32_16x16x32_bf16 v[28:31], v[80:83], v[182:185], v[28:31]
	v_mfma_f32_16x16x32_bf16 v[24:27], v[102:105], v[182:185], v[24:27]
	v_mfma_f32_16x16x32_bf16 v[12:15], v[80:83], v[196:199], v[12:15]
	v_mfma_f32_16x16x32_bf16 v[8:11], v[102:105], v[196:199], v[8:11]
	v_mfma_f32_16x16x32_bf16 v[60:63], v[88:91], v[164:167], v[60:63]
	v_mfma_f32_16x16x32_bf16 v[56:59], v[106:109], v[164:167], v[56:59]
	v_mfma_f32_16x16x32_bf16 v[44:47], v[88:91], v[172:175], v[44:47]
	v_mfma_f32_16x16x32_bf16 v[40:43], v[106:109], v[172:175], v[40:43]
	v_mfma_f32_16x16x32_bf16 v[28:31], v[88:91], v[186:189], v[28:31]
	v_mfma_f32_16x16x32_bf16 v[24:27], v[106:109], v[186:189], v[24:27]
	v_mfma_f32_16x16x32_bf16 v[12:15], v[88:91], v[200:203], v[12:15]
	v_mfma_f32_16x16x32_bf16 v[8:11], v[106:109], v[200:203], v[8:11]
	s_barrier
	s_setprio 0
	v_add_u32_e32 v96, 0x10000, v193
	ds_read_b128 v[80:83], v96
	ds_read_b128 v[88:91], v96 offset:1024
	ds_read_b128 v[102:105], v96 offset:2048
	ds_read_b128 v[106:109], v96 offset:3072
	s_add_u32 s60, s60, 0x40080
	s_addc_u32 s61, s61, 0
	s_add_i32 s62, s62, s18
	s_mov_b32 m0, s62
	s_nop 0
	global_load_lds_dwordx4 v150, s[60:61]
	s_add_i32 m0, s62, 0x2000
	s_nop 0
	global_load_lds_dwordx4 v146, s[60:61]
	s_waitcnt vmcnt(6)
	s_setprio 1
	s_barrier
	v_mfma_f32_16x16x32_bf16 v[52:55], v[224:227], v[160:163], v[52:55]
	v_mfma_f32_16x16x32_bf16 v[48:51], v[232:235], v[160:163], v[48:51]
	v_mfma_f32_16x16x32_bf16 v[36:39], v[224:227], v[168:171], v[36:39]
	s_add_i32 s71, s71, 2
	v_mfma_f32_16x16x32_bf16 v[32:35], v[232:235], v[168:171], v[32:35]
	s_add_u32 s58, s58, 0x100
	v_mfma_f32_16x16x32_bf16 v[20:23], v[224:227], v[182:185], v[20:23]
	s_addc_u32 s59, s59, 0
	v_mfma_f32_16x16x32_bf16 v[16:19], v[232:235], v[182:185], v[16:19]
	s_add_u32 s69, s69, 0x100
	v_mfma_f32_16x16x32_bf16 v[4:7], v[224:227], v[196:199], v[4:7]
	s_addc_u32 s70, s70, 0
	v_mfma_f32_16x16x32_bf16 v[0:3], v[232:235], v[196:199], v[0:3]
	s_cmp_gt_u32 s71, 13
	v_mfma_f32_16x16x32_bf16 v[52:55], v[228:231], v[164:167], v[52:55]
	v_mfma_f32_16x16x32_bf16 v[48:51], v[236:239], v[164:167], v[48:51]
	v_mfma_f32_16x16x32_bf16 v[36:39], v[228:231], v[172:175], v[36:39]
	v_mfma_f32_16x16x32_bf16 v[32:35], v[236:239], v[172:175], v[32:35]
	v_mfma_f32_16x16x32_bf16 v[20:23], v[228:231], v[186:189], v[20:23]
	v_mfma_f32_16x16x32_bf16 v[16:19], v[236:239], v[186:189], v[16:19]
	v_mfma_f32_16x16x32_bf16 v[4:7], v[228:231], v[200:203], v[4:7]
	v_mfma_f32_16x16x32_bf16 v[0:3], v[236:239], v[200:203], v[0:3]
	s_barrier
	s_setprio 0
	s_cbranch_scc0 .LBB0_557
	s_waitcnt lgkmcnt(0)
	s_lshl_b32 s47, s54, 8
	s_add_i32 s47, s47, s57
	v_or_b32_e32 v162, s47, v192
	s_lshl_b32 s100, s57, 2
	s_add_i32 s100, s100, 0x20000
	v_lshl_add_u32 v244, v192, 2, s100
	ds_read_b32 v245, v244 offset:64
	ds_read_b32 v246, v244 offset:128
	ds_read_b32 v247, v244 offset:192
	ds_read_b32 v248, v244 offset:512
	ds_read_b32 v249, v244 offset:576
	ds_read_b32 v250, v244 offset:640
	ds_read_b32 v251, v244 offset:704
	ds_read_b32 v244, v244
	v_or_b32_e32 v190, 16, v162
	v_or_b32_e32 v188, 32, v162
	v_or_b32_e32 v186, 48, v162
	v_add_u32_e32 v184, 0x80, v162
	v_add_u32_e32 v172, 0x90, v162
	v_add_u32_e32 v168, 0xa0, v162
	v_add_u32_e32 v164, 0xb0, v162
	s_cmpk_lt_u32 s47, 0x2000
	s_cselect_b32 s47, 1, 2
	v_mov_b32_e32 v218, s47
	v_cmp_lt_i32_e32 vcc, s23, v162
	v_lshl_or_b32 v166, s55, 8, v194
	v_ashrrev_i32_e32 v167, 31, v166
	v_cndmask_b32_e32 v185, 0, v218, vcc
	v_mul_u32_u24_e32 v82, 0x7600, v185
	v_lshlrev_b32_e32 v96, 2, v82
	v_lshl_add_u64 v[80:81], s[44:45], 0, v[96:97]
	v_lshl_add_u64 v[106:107], v[166:167], 2, v[80:81]
	global_load_dwordx4 v[80:83], v[106:107], off offset:16
	global_load_dwordx4 v[88:91], v[106:107], off
	global_load_dwordx4 v[102:105], v[106:107], off offset:528
	s_nop 0
	global_load_dwordx4 v[106:109], v[106:107], off offset:512
	v_lshl_or_b32 v160, s55, 7, v194
	v_cmp_lt_i32_e32 vcc, s23, v190
	s_waitcnt vmcnt(0)
	s_waitcnt lgkmcnt(0)
	v_mov_b32_e32 v96, v244
	v_mov_b64_e32 v[170:171], s[42:43]
	v_ashrrev_i32_e32 v161, 31, v160
	v_mad_i64_i32 v[170:171], s[54:55], v162, s31, v[170:171]
	v_lshl_add_u64 v[224:225], v[160:161], 1, v[170:171]
	v_pk_mul_f32 v[182:183], v[82:83], s[0:1] op_sel_hi:[1,0]
	v_pk_mul_f32 v[176:177], v[80:81], s[0:1] op_sel_hi:[1,0]
	v_pk_mul_f32 v[174:175], v[90:91], s[0:1] op_sel_hi:[1,0]
	v_pk_mul_f32 v[170:171], v[88:89], s[0:1] op_sel_hi:[1,0]
	v_mul_f32_e32 v226, 0xbfb8aa3b, v96
	v_pk_fma_f32 v[228:229], v[144:145], v[226:227], v[174:175] op_sel_hi:[1,0,1]
	v_pk_fma_f32 v[230:231], v[142:143], v[226:227], v[170:171] op_sel_hi:[1,0,1]
	v_pk_fma_f32 v[232:233], v[140:141], v[226:227], v[182:183] op_sel_hi:[1,0,1]
	v_pk_fma_f32 v[226:227], v[138:139], v[226:227], v[176:177] op_sel_hi:[1,0,1]
	v_exp_f32_e32 v230, v230
	v_exp_f32_e32 v226, v226
	v_exp_f32_e32 v231, v231
	v_exp_f32_e32 v227, v227
	v_exp_f32_e32 v232, v232
	v_exp_f32_e32 v233, v233
	v_exp_f32_e32 v228, v228
	v_exp_f32_e32 v229, v229
	v_pk_add_f32 v[230:231], v[230:231], 1.0 op_sel_hi:[1,0]
	v_pk_add_f32 v[232:233], v[232:233], 1.0 op_sel_hi:[1,0]
	v_pk_add_f32 v[226:227], v[226:227], 1.0 op_sel_hi:[1,0]
	v_pk_add_f32 v[228:229], v[228:229], 1.0 op_sel_hi:[1,0]
	v_rcp_f32_e32 v230, v230
	v_rcp_f32_e32 v226, v226
	v_rcp_f32_e32 v231, v231
	v_rcp_f32_e32 v227, v227
	v_rcp_f32_e32 v232, v232
	v_rcp_f32_e32 v233, v233
	v_rcp_f32_e32 v228, v228
	v_rcp_f32_e32 v229, v229
	v_pk_fma_f32 v[142:143], v[142:143], v[96:97], v[88:89] op_sel_hi:[1,0,1]
	v_pk_fma_f32 v[140:141], v[140:141], v[96:97], v[82:83] op_sel_hi:[1,0,1]
	v_pk_fma_f32 v[138:139], v[138:139], v[96:97], v[80:81] op_sel_hi:[1,0,1]
	v_pk_fma_f32 v[134:135], v[134:135], v[96:97], v[106:107] op_sel_hi:[1,0,1]
	v_pk_fma_f32 v[132:133], v[132:133], v[96:97], v[104:105] op_sel_hi:[1,0,1]
	v_pk_fma_f32 v[130:131], v[130:131], v[96:97], v[102:103] op_sel_hi:[1,0,1]
	v_pk_fma_f32 v[144:145], v[144:145], v[96:97], v[90:91] op_sel_hi:[1,0,1]
	v_pk_fma_f32 v[136:137], v[136:137], v[96:97], v[108:109] op_sel_hi:[1,0,1]
	v_pk_mul_f32 v[134:135], v[142:143], v[134:135]
	v_pk_mul_f32 v[132:133], v[140:141], v[132:133]
	v_pk_mul_f32 v[130:131], v[138:139], v[130:131]
	v_pk_mul_f32 v[136:137], v[144:145], v[136:137]
	v_pk_mul_f32 v[134:135], v[134:135], v[230:231]
	v_pk_mul_f32 v[138:139], v[132:133], v[232:233]
	v_pk_mul_f32 v[132:133], v[130:131], v[226:227]
	v_cvt_pk_bf16_f32 v130, v134, v135
	v_pk_mul_f32 v[136:137], v[136:137], v[228:229]
	v_cvt_pk_bf16_f32 v131, v136, v137
	v_cvt_pk_bf16_f32 v132, v132, v133
	v_cvt_pk_bf16_f32 v133, v138, v139
	global_store_dwordx4 v[224:225], v[130:133], off
	s_nop 0
	v_cndmask_b32_e32 v130, 0, v218, vcc
	v_cmp_ne_u32_e32 vcc, v130, v185
	s_and_saveexec_b64 s[54:55], vcc
	s_cbranch_execz .LBB0_560
	v_mul_u32_u24_e32 v80, 0x7600, v130
	v_lshlrev_b32_e32 v96, 2, v80
	v_lshl_add_u64 v[80:81], s[44:45], 0, v[96:97]
	v_lshl_add_u64 v[106:107], v[166:167], 2, v[80:81]
	global_load_dwordx4 v[88:91], v[106:107], off
	global_load_dwordx4 v[80:83], v[106:107], off offset:16
	global_load_dwordx4 v[102:105], v[106:107], off offset:528
	s_nop 0
	global_load_dwordx4 v[106:109], v[106:107], off offset:512
	v_mov_b32_e32 v185, v130
	s_waitcnt vmcnt(0)
	v_pk_mul_f32 v[170:171], v[88:89], s[0:1] op_sel_hi:[1,0]
	v_pk_mul_f32 v[174:175], v[90:91], s[0:1] op_sel_hi:[1,0]
	v_pk_mul_f32 v[176:177], v[80:81], s[0:1] op_sel_hi:[1,0]
	v_pk_mul_f32 v[182:183], v[82:83], s[0:1] op_sel_hi:[1,0]
.LBB0_560:
	s_or_b64 exec, exec, s[54:55]
	v_mov_b32_e32 v96, v245
	v_mov_b64_e32 v[130:131], s[42:43]
	v_mad_i64_i32 v[130:131], s[54:55], v190, s31, v[130:131]
	v_mul_f32_e32 v132, 0xbfb8aa3b, v96
	v_pk_fma_f32 v[134:135], v[128:129], v[132:133], v[174:175] op_sel_hi:[1,0,1]
	v_pk_fma_f32 v[136:137], v[126:127], v[132:133], v[170:171] op_sel_hi:[1,0,1]
	v_pk_fma_f32 v[138:139], v[124:125], v[132:133], v[182:183] op_sel_hi:[1,0,1]
	v_pk_fma_f32 v[132:133], v[122:123], v[132:133], v[176:177] op_sel_hi:[1,0,1]
	v_exp_f32_e32 v136, v136
	v_exp_f32_e32 v132, v132
	v_exp_f32_e32 v137, v137
	v_exp_f32_e32 v133, v133
	v_exp_f32_e32 v138, v138
	v_exp_f32_e32 v139, v139
	v_exp_f32_e32 v134, v134
	v_exp_f32_e32 v135, v135
	v_pk_add_f32 v[136:137], v[136:137], 1.0 op_sel_hi:[1,0]
	v_pk_add_f32 v[138:139], v[138:139], 1.0 op_sel_hi:[1,0]
	v_pk_add_f32 v[132:133], v[132:133], 1.0 op_sel_hi:[1,0]
	v_pk_add_f32 v[134:135], v[134:135], 1.0 op_sel_hi:[1,0]
	v_rcp_f32_e32 v136, v136
	v_rcp_f32_e32 v132, v132
	v_rcp_f32_e32 v137, v137
	v_rcp_f32_e32 v133, v133
	v_rcp_f32_e32 v138, v138
	v_rcp_f32_e32 v139, v139
	v_rcp_f32_e32 v134, v134
	v_rcp_f32_e32 v135, v135
	v_pk_fma_f32 v[126:127], v[126:127], v[96:97], v[88:89] op_sel_hi:[1,0,1]
	v_pk_fma_f32 v[124:125], v[124:125], v[96:97], v[82:83] op_sel_hi:[1,0,1]
	v_pk_fma_f32 v[122:123], v[122:123], v[96:97], v[80:81] op_sel_hi:[1,0,1]
	v_pk_fma_f32 v[118:119], v[118:119], v[96:97], v[106:107] op_sel_hi:[1,0,1]
	v_pk_fma_f32 v[116:117], v[116:117], v[96:97], v[104:105] op_sel_hi:[1,0,1]
	v_pk_fma_f32 v[114:115], v[114:115], v[96:97], v[102:103] op_sel_hi:[1,0,1]
	v_pk_fma_f32 v[128:129], v[128:129], v[96:97], v[90:91] op_sel_hi:[1,0,1]
	v_pk_fma_f32 v[120:121], v[120:121], v[96:97], v[108:109] op_sel_hi:[1,0,1]
	v_pk_mul_f32 v[118:119], v[118:119], v[126:127]
	v_pk_mul_f32 v[116:117], v[124:125], v[116:117]
	v_pk_mul_f32 v[114:115], v[122:123], v[114:115]
	v_lshl_add_u64 v[130:131], v[160:161], 1, v[130:131]
	v_pk_mul_f32 v[120:121], v[120:121], v[128:129]
	v_pk_mul_f32 v[118:119], v[118:119], v[136:137]
	v_pk_mul_f32 v[122:123], v[116:117], v[138:139]
	v_pk_mul_f32 v[116:117], v[114:115], v[132:133]
	v_cvt_pk_bf16_f32 v114, v118, v119
	v_mov_b32_e32 v96, s47
	v_cmp_lt_i32_e32 vcc, s23, v188
	v_pk_mul_f32 v[120:121], v[120:121], v[134:135]
	s_nop 0
	v_cvt_pk_bf16_f32 v115, v120, v121
	v_cvt_pk_bf16_f32 v116, v116, v117
	v_cvt_pk_bf16_f32 v117, v122, v123
	global_store_dwordx4 v[130:131], v[114:117], off
	s_nop 1
	v_cndmask_b32_e32 v114, 0, v96, vcc
	v_cmp_ne_u32_e32 vcc, v114, v185
	s_and_saveexec_b64 s[54:55], vcc
	s_movk_i32 s62, 0x3ff
	s_cbranch_execz .LBB0_562
	v_mul_u32_u24_e32 v80, 0x7600, v114
	v_lshlrev_b32_e32 v96, 2, v80
	v_lshl_add_u64 v[80:81], s[44:45], 0, v[96:97]
	v_lshl_add_u64 v[106:107], v[166:167], 2, v[80:81]
	global_load_dwordx4 v[88:91], v[106:107], off
	global_load_dwordx4 v[80:83], v[106:107], off offset:16
	global_load_dwordx4 v[102:105], v[106:107], off offset:528
	s_nop 0
	global_load_dwordx4 v[106:109], v[106:107], off offset:512
	v_mov_b32_e32 v185, v114
	s_waitcnt vmcnt(0)
	v_pk_mul_f32 v[170:171], v[88:89], s[0:1] op_sel_hi:[1,0]
	v_pk_mul_f32 v[174:175], v[90:91], s[0:1] op_sel_hi:[1,0]
	v_pk_mul_f32 v[176:177], v[80:81], s[0:1] op_sel_hi:[1,0]
	v_pk_mul_f32 v[182:183], v[82:83], s[0:1] op_sel_hi:[1,0]
.LBB0_562:
	s_or_b64 exec, exec, s[54:55]
	v_mov_b32_e32 v96, v246
	v_mov_b64_e32 v[114:115], s[42:43]
	v_mad_i64_i32 v[114:115], s[54:55], v188, s31, v[114:115]
	v_mul_f32_e32 v116, 0xbfb8aa3b, v96
	v_pk_fma_f32 v[118:119], v[112:113], v[116:117], v[174:175] op_sel_hi:[1,0,1]
	v_pk_fma_f32 v[120:121], v[110:111], v[116:117], v[170:171] op_sel_hi:[1,0,1]
	v_pk_fma_f32 v[122:123], v[100:101], v[116:117], v[182:183] op_sel_hi:[1,0,1]
	v_pk_fma_f32 v[116:117], v[98:99], v[116:117], v[176:177] op_sel_hi:[1,0,1]
	v_exp_f32_e32 v120, v120
	v_exp_f32_e32 v116, v116
	v_exp_f32_e32 v121, v121
	v_exp_f32_e32 v117, v117
	v_exp_f32_e32 v122, v122
	v_exp_f32_e32 v123, v123
	v_exp_f32_e32 v118, v118
	v_exp_f32_e32 v119, v119
	v_pk_add_f32 v[120:121], v[120:121], 1.0 op_sel_hi:[1,0]
	v_pk_add_f32 v[122:123], v[122:123], 1.0 op_sel_hi:[1,0]
	v_pk_add_f32 v[116:117], v[116:117], 1.0 op_sel_hi:[1,0]
	v_pk_add_f32 v[118:119], v[118:119], 1.0 op_sel_hi:[1,0]
	v_rcp_f32_e32 v120, v120
	v_rcp_f32_e32 v116, v116
	v_rcp_f32_e32 v121, v121
	v_rcp_f32_e32 v117, v117
	v_rcp_f32_e32 v122, v122
	v_rcp_f32_e32 v123, v123
	v_rcp_f32_e32 v118, v118
	v_rcp_f32_e32 v119, v119
	v_pk_fma_f32 v[110:111], v[110:111], v[96:97], v[88:89] op_sel_hi:[1,0,1]
	v_pk_fma_f32 v[100:101], v[100:101], v[96:97], v[82:83] op_sel_hi:[1,0,1]
	v_pk_fma_f32 v[98:99], v[98:99], v[96:97], v[80:81] op_sel_hi:[1,0,1]
	v_pk_fma_f32 v[92:93], v[92:93], v[96:97], v[106:107] op_sel_hi:[1,0,1]
	v_pk_fma_f32 v[86:87], v[86:87], v[96:97], v[104:105] op_sel_hi:[1,0,1]
	v_pk_fma_f32 v[84:85], v[84:85], v[96:97], v[102:103] op_sel_hi:[1,0,1]
	v_pk_fma_f32 v[112:113], v[112:113], v[96:97], v[90:91] op_sel_hi:[1,0,1]
	v_pk_fma_f32 v[94:95], v[94:95], v[96:97], v[108:109] op_sel_hi:[1,0,1]
	v_pk_mul_f32 v[92:93], v[92:93], v[110:111]
	v_pk_mul_f32 v[86:87], v[100:101], v[86:87]
	v_pk_mul_f32 v[84:85], v[98:99], v[84:85]
	v_lshl_add_u64 v[114:115], v[160:161], 1, v[114:115]
	v_pk_mul_f32 v[94:95], v[94:95], v[112:113]
	v_pk_mul_f32 v[92:93], v[92:93], v[120:121]
	v_pk_mul_f32 v[98:99], v[86:87], v[122:123]
	v_pk_mul_f32 v[86:87], v[84:85], v[116:117]
	v_cvt_pk_bf16_f32 v84, v92, v93
	v_pk_mul_f32 v[94:95], v[94:95], v[118:119]
	v_cmp_lt_i32_e32 vcc, s23, v186
	v_cvt_pk_bf16_f32 v85, v94, v95
	v_cvt_pk_bf16_f32 v86, v86, v87
	v_cvt_pk_bf16_f32 v87, v98, v99
	global_store_dwordx4 v[114:115], v[84:87], off
	s_nop 1
	v_mov_b32_e32 v84, s47
	v_cndmask_b32_e32 v84, 0, v84, vcc
	v_cmp_ne_u32_e32 vcc, v84, v185
	s_and_saveexec_b64 s[54:55], vcc
	s_cbranch_execz .LBB0_564
	v_mul_u32_u24_e32 v80, 0x7600, v84
	v_lshlrev_b32_e32 v96, 2, v80
	v_lshl_add_u64 v[80:81], s[44:45], 0, v[96:97]
	v_lshl_add_u64 v[86:87], v[166:167], 2, v[80:81]
	global_load_dwordx4 v[88:91], v[86:87], off
	global_load_dwordx4 v[80:83], v[86:87], off offset:16
	global_load_dwordx4 v[102:105], v[86:87], off offset:528
	global_load_dwordx4 v[106:109], v[86:87], off offset:512
	v_mov_b32_e32 v185, v84
	s_waitcnt vmcnt(0)
	v_pk_mul_f32 v[170:171], v[88:89], s[0:1] op_sel_hi:[1,0]
	v_pk_mul_f32 v[174:175], v[90:91], s[0:1] op_sel_hi:[1,0]
	v_pk_mul_f32 v[176:177], v[80:81], s[0:1] op_sel_hi:[1,0]
	v_pk_mul_f32 v[182:183], v[82:83], s[0:1] op_sel_hi:[1,0]
.LBB0_564:
	s_or_b64 exec, exec, s[54:55]
	v_mov_b32_e32 v86, v247
	v_mov_b64_e32 v[84:85], s[42:43]
	v_mad_i64_i32 v[84:85], s[54:55], v186, s31, v[84:85]
	v_mul_f32_e32 v92, 0xbfb8aa3b, v86
	v_pk_fma_f32 v[94:95], v[78:79], v[92:93], v[174:175] op_sel_hi:[1,0,1]
	v_pk_fma_f32 v[98:99], v[76:77], v[92:93], v[170:171] op_sel_hi:[1,0,1]
	v_pk_fma_f32 v[100:101], v[74:75], v[92:93], v[182:183] op_sel_hi:[1,0,1]
	v_pk_fma_f32 v[92:93], v[72:73], v[92:93], v[176:177] op_sel_hi:[1,0,1]
	v_exp_f32_e32 v98, v98
	v_exp_f32_e32 v92, v92
	v_exp_f32_e32 v99, v99
	v_exp_f32_e32 v93, v93
	v_exp_f32_e32 v100, v100
	v_exp_f32_e32 v101, v101
	v_exp_f32_e32 v94, v94
	v_exp_f32_e32 v95, v95
	v_pk_add_f32 v[98:99], v[98:99], 1.0 op_sel_hi:[1,0]
	v_pk_add_f32 v[100:101], v[100:101], 1.0 op_sel_hi:[1,0]
	v_pk_add_f32 v[92:93], v[92:93], 1.0 op_sel_hi:[1,0]
	v_pk_add_f32 v[94:95], v[94:95], 1.0 op_sel_hi:[1,0]
	v_rcp_f32_e32 v98, v98
	v_rcp_f32_e32 v92, v92
	v_rcp_f32_e32 v99, v99
	v_rcp_f32_e32 v93, v93
	v_rcp_f32_e32 v100, v100
	v_rcp_f32_e32 v101, v101
	v_rcp_f32_e32 v94, v94
	v_rcp_f32_e32 v95, v95
	v_pk_fma_f32 v[76:77], v[76:77], v[86:87], v[88:89] op_sel_hi:[1,0,1]
	v_pk_fma_f32 v[74:75], v[74:75], v[86:87], v[82:83] op_sel_hi:[1,0,1]
	v_pk_fma_f32 v[72:73], v[72:73], v[86:87], v[80:81] op_sel_hi:[1,0,1]
	v_pk_fma_f32 v[68:69], v[68:69], v[86:87], v[106:107] op_sel_hi:[1,0,1]
	v_pk_fma_f32 v[66:67], v[66:67], v[86:87], v[104:105] op_sel_hi:[1,0,1]
	v_pk_fma_f32 v[64:65], v[64:65], v[86:87], v[102:103] op_sel_hi:[1,0,1]
	v_pk_fma_f32 v[78:79], v[78:79], v[86:87], v[90:91] op_sel_hi:[1,0,1]
	v_pk_fma_f32 v[70:71], v[70:71], v[86:87], v[108:109] op_sel_hi:[1,0,1]
	v_pk_mul_f32 v[68:69], v[68:69], v[76:77]
	v_pk_mul_f32 v[66:67], v[74:75], v[66:67]
	v_pk_mul_f32 v[64:65], v[72:73], v[64:65]
	v_lshl_add_u64 v[84:85], v[160:161], 1, v[84:85]
	v_pk_mul_f32 v[70:71], v[70:71], v[78:79]
	v_pk_mul_f32 v[68:69], v[68:69], v[98:99]
	v_pk_mul_f32 v[72:73], v[66:67], v[100:101]
	v_pk_mul_f32 v[66:67], v[64:65], v[92:93]
	v_cvt_pk_bf16_f32 v64, v68, v69
	v_cmp_gt_u32_e32 vcc, s24, v184
	v_pk_mul_f32 v[70:71], v[70:71], v[94:95]
	s_nop 0
	v_cvt_pk_bf16_f32 v65, v70, v71
	v_cvt_pk_bf16_f32 v66, v66, v67
	v_cvt_pk_bf16_f32 v67, v72, v73
	global_store_dwordx4 v[84:85], v[64:67], off
	s_nop 1
	v_cndmask_b32_e64 v64, 2, 1, vcc
	v_cmp_lt_i32_e32 vcc, s30, v162
	s_nop 1
	v_cndmask_b32_e32 v64, 0, v64, vcc
	v_cmp_ne_u32_e32 vcc, v64, v185
	s_and_saveexec_b64 s[54:55], vcc
	s_cbranch_execz .LBB0_566
	v_mul_u32_u24_e32 v65, 0x7600, v64
	v_lshlrev_b32_e32 v96, 2, v65
	v_lshl_add_u64 v[66:67], s[44:45], 0, v[96:97]
	v_lshl_add_u64 v[66:67], v[166:167], 2, v[66:67]
	global_load_dwordx4 v[88:91], v[66:67], off
	global_load_dwordx4 v[80:83], v[66:67], off offset:16
	global_load_dwordx4 v[102:105], v[66:67], off offset:528
	global_load_dwordx4 v[106:109], v[66:67], off offset:512
	v_mov_b32_e32 v185, v64
	s_waitcnt vmcnt(0)
	v_pk_mul_f32 v[170:171], v[88:89], s[0:1] op_sel_hi:[1,0]
	v_pk_mul_f32 v[174:175], v[90:91], s[0:1] op_sel_hi:[1,0]
	v_pk_mul_f32 v[176:177], v[80:81], s[0:1] op_sel_hi:[1,0]
	v_pk_mul_f32 v[182:183], v[82:83], s[0:1] op_sel_hi:[1,0]
.LBB0_566:
	s_or_b64 exec, exec, s[54:55]
	v_mov_b32_e32 v66, v248
	v_mov_b64_e32 v[64:65], s[42:43]
	v_mad_i64_i32 v[64:65], s[54:55], v184, s31, v[64:65]
	v_mul_f32_e32 v68, 0xbfb8aa3b, v66
	v_pk_fma_f32 v[70:71], v[62:63], v[68:69], v[174:175] op_sel_hi:[1,0,1]
	v_pk_fma_f32 v[72:73], v[60:61], v[68:69], v[170:171] op_sel_hi:[1,0,1]
	v_pk_fma_f32 v[74:75], v[58:59], v[68:69], v[182:183] op_sel_hi:[1,0,1]
	v_pk_fma_f32 v[68:69], v[56:57], v[68:69], v[176:177] op_sel_hi:[1,0,1]
	v_exp_f32_e32 v72, v72
	v_exp_f32_e32 v68, v68
	v_exp_f32_e32 v73, v73
	v_exp_f32_e32 v69, v69
	v_exp_f32_e32 v74, v74
	v_exp_f32_e32 v75, v75
	v_exp_f32_e32 v70, v70
	v_exp_f32_e32 v71, v71
	v_pk_add_f32 v[72:73], v[72:73], 1.0 op_sel_hi:[1,0]
	v_pk_add_f32 v[74:75], v[74:75], 1.0 op_sel_hi:[1,0]
	v_pk_add_f32 v[68:69], v[68:69], 1.0 op_sel_hi:[1,0]
	v_pk_add_f32 v[70:71], v[70:71], 1.0 op_sel_hi:[1,0]
	v_rcp_f32_e32 v72, v72
	v_rcp_f32_e32 v68, v68
	v_rcp_f32_e32 v73, v73
	v_rcp_f32_e32 v69, v69
	v_rcp_f32_e32 v74, v74
	v_rcp_f32_e32 v75, v75
	v_rcp_f32_e32 v70, v70
	v_rcp_f32_e32 v71, v71
	v_pk_fma_f32 v[60:61], v[60:61], v[66:67], v[88:89] op_sel_hi:[1,0,1]
	v_pk_fma_f32 v[58:59], v[58:59], v[66:67], v[82:83] op_sel_hi:[1,0,1]
	v_pk_fma_f32 v[56:57], v[56:57], v[66:67], v[80:81] op_sel_hi:[1,0,1]
	v_pk_fma_f32 v[52:53], v[52:53], v[66:67], v[106:107] op_sel_hi:[1,0,1]
	v_pk_fma_f32 v[50:51], v[50:51], v[66:67], v[104:105] op_sel_hi:[1,0,1]
	v_pk_fma_f32 v[48:49], v[48:49], v[66:67], v[102:103] op_sel_hi:[1,0,1]
	v_pk_fma_f32 v[62:63], v[62:63], v[66:67], v[90:91] op_sel_hi:[1,0,1]
	v_pk_fma_f32 v[54:55], v[54:55], v[66:67], v[108:109] op_sel_hi:[1,0,1]
	v_pk_mul_f32 v[52:53], v[52:53], v[60:61]
	v_pk_mul_f32 v[50:51], v[58:59], v[50:51]
	v_pk_mul_f32 v[48:49], v[56:57], v[48:49]
	v_lshl_add_u64 v[64:65], v[160:161], 1, v[64:65]
	v_pk_mul_f32 v[54:55], v[54:55], v[62:63]
	v_pk_mul_f32 v[52:53], v[52:53], v[72:73]
	v_pk_mul_f32 v[56:57], v[50:51], v[74:75]
	v_pk_mul_f32 v[50:51], v[48:49], v[68:69]
	v_cvt_pk_bf16_f32 v48, v52, v53
	v_cmp_gt_u32_e32 vcc, s24, v172
	s_movk_i32 s47, 0xf6f
	v_pk_mul_f32 v[54:55], v[54:55], v[70:71]
	s_nop 0
	v_cvt_pk_bf16_f32 v49, v54, v55
	v_cvt_pk_bf16_f32 v50, v50, v51
	v_cvt_pk_bf16_f32 v51, v56, v57
	global_store_dwordx4 v[64:65], v[48:51], off
	s_nop 1
	v_cndmask_b32_e64 v48, 2, 1, vcc
	v_cmp_lt_i32_e32 vcc, s47, v162
	s_nop 1
	v_cndmask_b32_e32 v48, 0, v48, vcc
	v_cmp_ne_u32_e32 vcc, v48, v185
	s_and_saveexec_b64 s[54:55], vcc
	s_cbranch_execz .LBB0_568
	v_mul_u32_u24_e32 v49, 0x7600, v48
	v_lshlrev_b32_e32 v96, 2, v49
	v_lshl_add_u64 v[50:51], s[44:45], 0, v[96:97]
	v_lshl_add_u64 v[50:51], v[166:167], 2, v[50:51]
	global_load_dwordx4 v[88:91], v[50:51], off
	global_load_dwordx4 v[80:83], v[50:51], off offset:16
	global_load_dwordx4 v[102:105], v[50:51], off offset:528
	global_load_dwordx4 v[106:109], v[50:51], off offset:512
	v_mov_b32_e32 v185, v48
	s_waitcnt vmcnt(0)
	v_pk_mul_f32 v[170:171], v[88:89], s[0:1] op_sel_hi:[1,0]
	v_pk_mul_f32 v[174:175], v[90:91], s[0:1] op_sel_hi:[1,0]
	v_pk_mul_f32 v[176:177], v[80:81], s[0:1] op_sel_hi:[1,0]
	v_pk_mul_f32 v[182:183], v[82:83], s[0:1] op_sel_hi:[1,0]
.LBB0_568:
	s_or_b64 exec, exec, s[54:55]
	v_mov_b32_e32 v50, v249
	v_mov_b64_e32 v[48:49], s[42:43]
	v_mad_i64_i32 v[48:49], s[54:55], v172, s31, v[48:49]
	v_mul_f32_e32 v52, 0xbfb8aa3b, v50
	v_pk_fma_f32 v[54:55], v[46:47], v[52:53], v[174:175] op_sel_hi:[1,0,1]
	v_pk_fma_f32 v[56:57], v[44:45], v[52:53], v[170:171] op_sel_hi:[1,0,1]
	v_pk_fma_f32 v[58:59], v[42:43], v[52:53], v[182:183] op_sel_hi:[1,0,1]
	v_pk_fma_f32 v[52:53], v[40:41], v[52:53], v[176:177] op_sel_hi:[1,0,1]
	v_exp_f32_e32 v56, v56
	v_exp_f32_e32 v52, v52
	v_exp_f32_e32 v57, v57
	v_exp_f32_e32 v53, v53
	v_exp_f32_e32 v58, v58
	v_exp_f32_e32 v59, v59
	v_exp_f32_e32 v54, v54
	v_exp_f32_e32 v55, v55
	v_pk_add_f32 v[56:57], v[56:57], 1.0 op_sel_hi:[1,0]
	v_pk_add_f32 v[58:59], v[58:59], 1.0 op_sel_hi:[1,0]
	v_pk_add_f32 v[52:53], v[52:53], 1.0 op_sel_hi:[1,0]
	v_pk_add_f32 v[54:55], v[54:55], 1.0 op_sel_hi:[1,0]
	v_rcp_f32_e32 v56, v56
	v_rcp_f32_e32 v52, v52
	v_rcp_f32_e32 v57, v57
	v_rcp_f32_e32 v53, v53
	v_rcp_f32_e32 v58, v58
	v_rcp_f32_e32 v59, v59
	v_rcp_f32_e32 v54, v54
	v_rcp_f32_e32 v55, v55
	v_pk_fma_f32 v[44:45], v[44:45], v[50:51], v[88:89] op_sel_hi:[1,0,1]
	v_pk_fma_f32 v[42:43], v[42:43], v[50:51], v[82:83] op_sel_hi:[1,0,1]
	v_pk_fma_f32 v[40:41], v[40:41], v[50:51], v[80:81] op_sel_hi:[1,0,1]
	v_pk_fma_f32 v[36:37], v[36:37], v[50:51], v[106:107] op_sel_hi:[1,0,1]
	v_pk_fma_f32 v[34:35], v[34:35], v[50:51], v[104:105] op_sel_hi:[1,0,1]
	v_pk_fma_f32 v[32:33], v[32:33], v[50:51], v[102:103] op_sel_hi:[1,0,1]
	v_pk_fma_f32 v[46:47], v[46:47], v[50:51], v[90:91] op_sel_hi:[1,0,1]
	v_pk_fma_f32 v[38:39], v[38:39], v[50:51], v[108:109] op_sel_hi:[1,0,1]
	v_pk_mul_f32 v[36:37], v[36:37], v[44:45]
	v_pk_mul_f32 v[34:35], v[42:43], v[34:35]
	v_pk_mul_f32 v[32:33], v[40:41], v[32:33]
	v_lshl_add_u64 v[48:49], v[160:161], 1, v[48:49]
	v_pk_mul_f32 v[38:39], v[38:39], v[46:47]
	v_pk_mul_f32 v[36:37], v[36:37], v[56:57]
	v_pk_mul_f32 v[40:41], v[34:35], v[58:59]
	v_pk_mul_f32 v[34:35], v[32:33], v[52:53]
	v_cvt_pk_bf16_f32 v32, v36, v37
	v_cmp_gt_u32_e32 vcc, s24, v168
	s_movk_i32 s47, 0xf5f
	v_pk_mul_f32 v[38:39], v[38:39], v[54:55]
	s_nop 0
	v_cvt_pk_bf16_f32 v33, v38, v39
	v_cvt_pk_bf16_f32 v34, v34, v35
	v_cvt_pk_bf16_f32 v35, v40, v41
	global_store_dwordx4 v[48:49], v[32:35], off
	s_nop 1
	v_cndmask_b32_e64 v32, 2, 1, vcc
	v_cmp_lt_i32_e32 vcc, s47, v162
	s_nop 1
	v_cndmask_b32_e32 v32, 0, v32, vcc
	v_cmp_ne_u32_e32 vcc, v32, v185
	s_and_saveexec_b64 s[54:55], vcc
	s_cbranch_execz .LBB0_570
	v_mul_u32_u24_e32 v33, 0x7600, v32
	v_lshlrev_b32_e32 v96, 2, v33
	v_lshl_add_u64 v[34:35], s[44:45], 0, v[96:97]
	v_lshl_add_u64 v[34:35], v[166:167], 2, v[34:35]
	global_load_dwordx4 v[88:91], v[34:35], off
	global_load_dwordx4 v[80:83], v[34:35], off offset:16
	global_load_dwordx4 v[102:105], v[34:35], off offset:528
	global_load_dwordx4 v[106:109], v[34:35], off offset:512
	v_mov_b32_e32 v185, v32
	s_waitcnt vmcnt(0)
	v_pk_mul_f32 v[170:171], v[88:89], s[0:1] op_sel_hi:[1,0]
	v_pk_mul_f32 v[174:175], v[90:91], s[0:1] op_sel_hi:[1,0]
	v_pk_mul_f32 v[176:177], v[80:81], s[0:1] op_sel_hi:[1,0]
	v_pk_mul_f32 v[182:183], v[82:83], s[0:1] op_sel_hi:[1,0]
.LBB0_570:
	s_or_b64 exec, exec, s[54:55]
	v_mov_b32_e32 v34, v250
	v_mov_b64_e32 v[32:33], s[42:43]
	v_mad_i64_i32 v[32:33], s[54:55], v168, s31, v[32:33]
	v_mul_f32_e32 v36, 0xbfb8aa3b, v34
	v_pk_fma_f32 v[38:39], v[30:31], v[36:37], v[174:175] op_sel_hi:[1,0,1]
	v_pk_fma_f32 v[40:41], v[28:29], v[36:37], v[170:171] op_sel_hi:[1,0,1]
	v_pk_fma_f32 v[42:43], v[26:27], v[36:37], v[182:183] op_sel_hi:[1,0,1]
	v_pk_fma_f32 v[36:37], v[24:25], v[36:37], v[176:177] op_sel_hi:[1,0,1]
	v_exp_f32_e32 v40, v40
	v_exp_f32_e32 v36, v36
	v_exp_f32_e32 v41, v41
	v_exp_f32_e32 v37, v37
	v_exp_f32_e32 v42, v42
	v_exp_f32_e32 v43, v43
	v_exp_f32_e32 v38, v38
	v_exp_f32_e32 v39, v39
	v_pk_add_f32 v[40:41], v[40:41], 1.0 op_sel_hi:[1,0]
	v_pk_add_f32 v[42:43], v[42:43], 1.0 op_sel_hi:[1,0]
	v_pk_add_f32 v[36:37], v[36:37], 1.0 op_sel_hi:[1,0]
	v_pk_add_f32 v[38:39], v[38:39], 1.0 op_sel_hi:[1,0]
	v_rcp_f32_e32 v40, v40
	v_rcp_f32_e32 v36, v36
	v_rcp_f32_e32 v41, v41
	v_rcp_f32_e32 v37, v37
	v_rcp_f32_e32 v42, v42
	v_rcp_f32_e32 v43, v43
	v_rcp_f32_e32 v38, v38
	v_rcp_f32_e32 v39, v39
	v_pk_fma_f32 v[28:29], v[28:29], v[34:35], v[88:89] op_sel_hi:[1,0,1]
	v_pk_fma_f32 v[26:27], v[26:27], v[34:35], v[82:83] op_sel_hi:[1,0,1]
	v_pk_fma_f32 v[24:25], v[24:25], v[34:35], v[80:81] op_sel_hi:[1,0,1]
	v_pk_fma_f32 v[20:21], v[20:21], v[34:35], v[106:107] op_sel_hi:[1,0,1]
	v_pk_fma_f32 v[18:19], v[18:19], v[34:35], v[104:105] op_sel_hi:[1,0,1]
	v_pk_fma_f32 v[16:17], v[16:17], v[34:35], v[102:103] op_sel_hi:[1,0,1]
	v_pk_fma_f32 v[30:31], v[30:31], v[34:35], v[90:91] op_sel_hi:[1,0,1]
	v_pk_fma_f32 v[22:23], v[22:23], v[34:35], v[108:109] op_sel_hi:[1,0,1]
	v_pk_mul_f32 v[20:21], v[20:21], v[28:29]
	v_pk_mul_f32 v[18:19], v[26:27], v[18:19]
	v_pk_mul_f32 v[16:17], v[24:25], v[16:17]
	v_lshl_add_u64 v[32:33], v[160:161], 1, v[32:33]
	v_pk_mul_f32 v[22:23], v[22:23], v[30:31]
	v_pk_mul_f32 v[20:21], v[20:21], v[40:41]
	v_pk_mul_f32 v[24:25], v[18:19], v[42:43]
	v_pk_mul_f32 v[18:19], v[16:17], v[36:37]
	v_cvt_pk_bf16_f32 v16, v20, v21
	v_cmp_gt_u32_e32 vcc, s24, v164
	s_movk_i32 s47, 0xf4f
	v_pk_mul_f32 v[22:23], v[22:23], v[38:39]
	s_nop 0
	v_cvt_pk_bf16_f32 v17, v22, v23
	v_cvt_pk_bf16_f32 v18, v18, v19
	v_cvt_pk_bf16_f32 v19, v24, v25
	global_store_dwordx4 v[32:33], v[16:19], off
	s_nop 1
	v_cndmask_b32_e64 v16, 2, 1, vcc
	v_cmp_lt_i32_e32 vcc, s47, v162
	s_nop 1
	v_cndmask_b32_e32 v16, 0, v16, vcc
	v_cmp_ne_u32_e32 vcc, v16, v185
	s_and_saveexec_b64 s[54:55], vcc
	s_cbranch_execz .LBB0_553
	v_mul_u32_u24_e32 v16, 0x7600, v16
	v_lshlrev_b32_e32 v96, 2, v16
	v_lshl_add_u64 v[16:17], s[44:45], 0, v[96:97]
	v_lshl_add_u64 v[16:17], v[166:167], 2, v[16:17]
	global_load_dwordx4 v[88:91], v[16:17], off
	global_load_dwordx4 v[80:83], v[16:17], off offset:16
	global_load_dwordx4 v[102:105], v[16:17], off offset:528
	global_load_dwordx4 v[106:109], v[16:17], off offset:512
	s_waitcnt vmcnt(0)
	v_pk_mul_f32 v[170:171], v[88:89], s[0:1] op_sel_hi:[1,0]
	v_pk_mul_f32 v[174:175], v[90:91], s[0:1] op_sel_hi:[1,0]
	v_pk_mul_f32 v[176:177], v[80:81], s[0:1] op_sel_hi:[1,0]
	v_pk_mul_f32 v[182:183], v[82:83], s[0:1] op_sel_hi:[1,0]
	s_branch .LBB0_553
